# P0: each wave's four x rows (16 loads) prefetched at the start of P0 into v182-245 and copied at the conversion (latency under the weight transposes); on top of v95
# speedup vs baseline: 1.0013x; 1.0001x over previous
; #define GAS __attribute__((address_space(1)))
; __global__ void __launch_bounds__(NWAVES * 64, 2) fwd_kernel(Args args) {
;     ...
;         for (int m0 = 4 * gw; m0 < P0_XROWS; m0 += 4 * NGW) {
;             f32x4 v[4][4];
; #pragma unroll
;             for (int rr = 0; rr < 4; ++rr) { const GAS f32x4* xr = (const GAS f32x4*)(x + (size_t)(m0 + rr) * DM) + F.lane;
; #pragma unroll
;                 for (int j = 0; j < 4; ++j) v[rr][j] = __builtin_nontemporal_load(xr + 64 * j); }
.LBB0_10:
	v_writelane_b32 v253, s12, 6
	s_cmp_lt_i32 s66, 1
	s_cselect_b64 s[0:1], -1, 0
	v_writelane_b32 v253, s13, 7
	s_cmp_gt_i32 s67, 0
	v_writelane_b32 v253, s14, 8
	s_cselect_b64 s[4:5], -1, 0
	v_writelane_b32 v253, s15, 9
	s_and_b64 s[0:1], s[0:1], s[4:5]
	v_writelane_b32 v253, s16, 10
	s_add_u32 s30, s42, 0x2200000
	v_writelane_b32 v253, s17, 11
	s_addc_u32 s31, s43, 0
	v_writelane_b32 v253, s18, 12
	s_add_u32 s4, s42, 0x1a00000
	v_writelane_b32 v253, s19, 13
	s_addc_u32 s5, s43, 0
	v_writelane_b32 v253, s4, 14
	s_mov_b32 s89, 0
	s_nop 0
	v_writelane_b32 v253, s5, 15
	s_add_u32 s4, s42, 0x1800000
	s_addc_u32 s5, s43, 0
	v_writelane_b32 v253, s4, 16
	s_nop 1
	v_writelane_b32 v253, s5, 17
	s_add_u32 s4, s42, 0x400000
	s_addc_u32 s5, s43, 0
	v_writelane_b32 v253, s4, 18
	s_nop 1
	v_writelane_b32 v253, s5, 19
	s_add_u32 s4, s42, 0x180000
	s_addc_u32 s5, s43, 0
	v_writelane_b32 v253, s4, 20
	s_cmp_eq_u32 s6, 15
	s_nop 0
	v_writelane_b32 v253, s5, 21
	s_cselect_b64 s[4:5], -1, 0
	v_writelane_b32 v253, s4, 22
	s_cmp_eq_u32 s6, 14
	s_nop 0
	v_writelane_b32 v253, s5, 23
	s_cselect_b64 s[4:5], -1, 0
	v_writelane_b32 v253, s4, 24
	s_cmp_eq_u32 s6, 13
	s_nop 0
	v_writelane_b32 v253, s5, 25
	s_cselect_b64 s[4:5], -1, 0
	v_writelane_b32 v253, s4, 26
	s_cmp_eq_u32 s6, 12
	s_nop 0
	v_writelane_b32 v253, s5, 27
	s_cselect_b64 s[4:5], -1, 0
	v_writelane_b32 v253, s4, 28
	s_cmp_eq_u32 s6, 11
	s_nop 0
	v_writelane_b32 v253, s5, 29
	s_cselect_b64 s[4:5], -1, 0
	v_writelane_b32 v253, s4, 30
	s_cmp_eq_u32 s6, 10
	s_nop 0
	v_writelane_b32 v253, s5, 31
	s_cselect_b64 s[4:5], -1, 0
	v_writelane_b32 v253, s4, 32
	s_cmp_eq_u32 s6, 9
	s_nop 0
	v_writelane_b32 v253, s5, 33
	s_cselect_b64 s[4:5], -1, 0
	v_writelane_b32 v253, s4, 34
	s_cmp_eq_u32 s6, 8
	s_nop 0
	v_writelane_b32 v253, s5, 35
	s_cselect_b64 s[4:5], -1, 0
	v_writelane_b32 v253, s4, 36
	s_cmp_eq_u32 s6, 7
	s_nop 0
	v_writelane_b32 v253, s5, 37
	s_cselect_b64 s[4:5], -1, 0
	v_writelane_b32 v253, s4, 38
	s_cmp_eq_u32 s6, 6
	s_nop 0
	v_writelane_b32 v253, s5, 39
	s_cselect_b64 s[4:5], -1, 0
	v_writelane_b32 v253, s4, 40
	s_cmp_eq_u32 s6, 5
	s_nop 0
	v_writelane_b32 v253, s5, 41
	s_cselect_b64 s[4:5], -1, 0
	v_writelane_b32 v253, s4, 42
	s_cmp_eq_u32 s6, 4
	s_nop 0
	v_writelane_b32 v253, s5, 43
	s_cselect_b64 s[4:5], -1, 0
	v_writelane_b32 v253, s4, 44
	s_cmp_eq_u32 s6, 3
	s_nop 0
	v_writelane_b32 v253, s5, 45
	s_cselect_b64 s[4:5], -1, 0
	v_writelane_b32 v253, s4, 46
	s_cmp_eq_u32 s6, 2
	s_nop 0
	v_writelane_b32 v253, s5, 47
	s_cselect_b64 s[4:5], -1, 0
	v_writelane_b32 v253, s4, 48
	s_cmp_eq_u32 s6, 1
	s_nop 0
	v_writelane_b32 v253, s5, 49
	s_cselect_b64 s[4:5], -1, 0
	v_writelane_b32 v253, s4, 50
	s_cmp_eq_u32 s6, 0
	s_nop 0
	v_writelane_b32 v253, s5, 51
	s_cselect_b64 s[4:5], -1, 0
	v_writelane_b32 v253, s4, 52
	s_and_b64 vcc, exec, s[0:1]
	s_nop 0
	v_writelane_b32 v253, s5, 53
	s_lshl_b32 s4, s6, 6
	v_writelane_b32 v253, s4, 54
	s_cbranch_vccz .LBB0_185
	s_lshl_b32 s14, s60, 3
	v_mbcnt_lo_u32_b32 v0, -1, 0
	v_mbcnt_hi_u32_b32 v0, -1, v0
	s_add_i32 s14, s14, s2
	v_add_u32_e32 v64, s65, v0
	s_lshl_b32 s100, s14, 2
	s_cmpk_gt_i32 s100, 0x1fff
	s_cbranch_scc1 .Lxr_nopf
	s_lshl_b32 s100, s14, 14
	s_add_u32 vcc_lo, s44, s100
	s_addc_u32 vcc_hi, s45, 0
	v_and_b32_e32 v246, 63, v64
	v_lshlrev_b32_e32 v246, 4, v246
	global_load_dwordx4 v[194:197], v246, vcc nt
	global_load_dwordx4 v[190:193], v246, vcc offset:1024 nt
	global_load_dwordx4 v[186:189], v246, vcc offset:2048 nt
	global_load_dwordx4 v[182:185], v246, vcc offset:3072 nt
	v_add_u32_e32 v246, 0x1000, v246
	global_load_dwordx4 v[242:245], v246, vcc nt
	global_load_dwordx4 v[238:241], v246, vcc offset:1024 nt
	global_load_dwordx4 v[234:237], v246, vcc offset:2048 nt
	global_load_dwordx4 v[230:233], v246, vcc offset:3072 nt
	v_add_u32_e32 v246, 0x1000, v246
	global_load_dwordx4 v[226:229], v246, vcc nt
	global_load_dwordx4 v[222:225], v246, vcc offset:1024 nt
	global_load_dwordx4 v[218:221], v246, vcc offset:2048 nt
	global_load_dwordx4 v[214:217], v246, vcc offset:3072 nt
	v_add_u32_e32 v246, 0x1000, v246
	global_load_dwordx4 v[210:213], v246, vcc nt
	global_load_dwordx4 v[206:209], v246, vcc offset:1024 nt
	global_load_dwordx4 v[202:205], v246, vcc offset:2048 nt
	global_load_dwordx4 v[198:201], v246, vcc offset:3072 nt

; __device__ __forceinline__ float wave_sum(float v) { v += dpp_mov<0xB1>(v); v += dpp_mov<0x4E>(v); v += dpp_mov<0x141>(v); v += dpp_mov<0x140>(v); v = sum_x16(v); return sum_x32(v); }
; #define GAS __attribute__((address_space(1)))
; __global__ void __launch_bounds__(NWAVES * 64, 2) fwd_kernel(Args args) {
;     ...
;         for (int m0 = 4 * gw; m0 < P0_XROWS; m0 += 4 * NGW) {
;             f32x4 v[4][4];
; #pragma unroll
;             for (int rr = 0; rr < 4; ++rr) { const GAS f32x4* xr = (const GAS f32x4*)(x + (size_t)(m0 + rr) * DM) + F.lane;
; #pragma unroll
;                 for (int j = 0; j < 4; ++j) v[rr][j] = __builtin_nontemporal_load(xr + 64 * j); }
; #pragma unroll
;             for (int rr = 0; rr < 4; ++rr) {
;                 float s = 0.f;
; #pragma unroll
;                 for (int j = 0; j < 4; ++j) s += (v[rr][j].x * v[rr][j].x + v[rr][j].y * v[rr][j].y) + (v[rr][j].z * v[rr][j].z + v[rr][j].w * v[rr][j].w);
;                 s = wave_sum(s);
.LBB0_60:
	s_cmpk_lt_u32 s4, 0x2000
	s_cselect_b64 exec, -1, 0
	v_add_co_u32_e32 v16, vcc, 0x1000, v68
	global_load_dwordx4 v[12:15], v[68:69], off nt
	global_load_dwordx4 v[8:11], v[68:69], off offset:1024 nt
	global_load_dwordx4 v[4:7], v[68:69], off offset:2048 nt
	global_load_dwordx4 v[0:3], v[68:69], off offset:3072 nt
	v_addc_co_u32_e32 v17, vcc, 0, v69, vcc
	v_add_co_u32_e32 v18, vcc, 0x2000, v68
	global_load_dwordx4 v[60:63], v[16:17], off nt
	global_load_dwordx4 v[56:59], v[16:17], off offset:1024 nt
	global_load_dwordx4 v[52:55], v[16:17], off offset:2048 nt
	global_load_dwordx4 v[48:51], v[16:17], off offset:3072 nt
	v_addc_co_u32_e32 v19, vcc, 0, v69, vcc
	v_add_co_u32_e32 v16, vcc, 0x3000, v68
	global_load_dwordx4 v[44:47], v[18:19], off nt
	global_load_dwordx4 v[40:43], v[18:19], off offset:1024 nt
	global_load_dwordx4 v[36:39], v[18:19], off offset:2048 nt
	global_load_dwordx4 v[32:35], v[18:19], off offset:3072 nt
	v_addc_co_u32_e32 v17, vcc, 0, v69, vcc
	global_load_dwordx4 v[28:31], v[16:17], off nt
	global_load_dwordx4 v[24:27], v[16:17], off offset:1024 nt
	global_load_dwordx4 v[20:23], v[16:17], off offset:2048 nt
	s_nop 0
	global_load_dwordx4 v[16:19], v[16:17], off offset:3072 nt
	s_mov_b64 exec, -1
	s_cbranch_scc1 .Lxr_go
	s_waitcnt vmcnt(0)
	v_mov_b32_e32 v0, v182
	v_mov_b32_e32 v1, v183
	v_mov_b32_e32 v2, v184
	v_mov_b32_e32 v3, v185
	v_mov_b32_e32 v4, v186
	v_mov_b32_e32 v5, v187
	v_mov_b32_e32 v6, v188
	v_mov_b32_e32 v7, v189
	v_mov_b32_e32 v8, v190
	v_mov_b32_e32 v9, v191
	v_mov_b32_e32 v10, v192
	v_mov_b32_e32 v11, v193
	v_mov_b32_e32 v12, v194
	v_mov_b32_e32 v13, v195
	v_mov_b32_e32 v14, v196
	v_mov_b32_e32 v15, v197
	v_mov_b32_e32 v16, v198
	v_mov_b32_e32 v17, v199
	v_mov_b32_e32 v18, v200
	v_mov_b32_e32 v19, v201
	v_mov_b32_e32 v20, v202
	v_mov_b32_e32 v21, v203
	v_mov_b32_e32 v22, v204
	v_mov_b32_e32 v23, v205
	v_mov_b32_e32 v24, v206
	v_mov_b32_e32 v25, v207
	v_mov_b32_e32 v26, v208
	v_mov_b32_e32 v27, v209
	v_mov_b32_e32 v28, v210
	v_mov_b32_e32 v29, v211
	v_mov_b32_e32 v30, v212
	v_mov_b32_e32 v31, v213
	v_mov_b32_e32 v32, v214
	v_mov_b32_e32 v33, v215
	v_mov_b32_e32 v34, v216
	v_mov_b32_e32 v35, v217
	v_mov_b32_e32 v36, v218
	v_mov_b32_e32 v37, v219
	v_mov_b32_e32 v38, v220
	v_mov_b32_e32 v39, v221
	v_mov_b32_e32 v40, v222
	v_mov_b32_e32 v41, v223
	v_mov_b32_e32 v42, v224
	v_mov_b32_e32 v43, v225
	v_mov_b32_e32 v44, v226
	v_mov_b32_e32 v45, v227
	v_mov_b32_e32 v46, v228
	v_mov_b32_e32 v47, v229
	v_mov_b32_e32 v48, v230
	v_mov_b32_e32 v49, v231
	v_mov_b32_e32 v50, v232
	v_mov_b32_e32 v51, v233
	v_mov_b32_e32 v52, v234
	v_mov_b32_e32 v53, v235
	v_mov_b32_e32 v54, v236
	v_mov_b32_e32 v55, v237
	v_mov_b32_e32 v56, v238
	v_mov_b32_e32 v57, v239
	v_mov_b32_e32 v58, v240
	v_mov_b32_e32 v59, v241
	v_mov_b32_e32 v60, v242
	v_mov_b32_e32 v61, v243
	v_mov_b32_e32 v62, v244
	v_mov_b32_e32 v63, v245
.Lxr_go:
	v_add_co_u32_e64 v70, s[34:35], s1, v66
	s_add_i32 s0, s0, s4
	s_nop 0
	v_addc_co_u32_e64 v71, s[34:35], 0, v67, s[34:35]
	s_cmpk_gt_i32 s0, 0x1fff
	v_lshl_add_u64 v[68:69], v[68:69], 0, s[8:9]
	s_waitcnt vmcnt(15)
	v_mul_f32_e32 v82, v13, v13
	v_mul_f32_e32 v83, v15, v15
	s_waitcnt vmcnt(14)
	v_mul_f32_e32 v84, v9, v9
	v_mul_f32_e32 v85, v11, v11
	s_waitcnt vmcnt(13)
	v_mul_f32_e32 v86, v5, v5
	v_mul_f32_e32 v87, v7, v7
	s_waitcnt vmcnt(12)
	v_mul_f32_e32 v88, v1, v1
	v_mul_f32_e32 v89, v3, v3
	v_fmac_f32_e32 v82, v12, v12
	v_fmac_f32_e32 v83, v14, v14
	v_fmac_f32_e32 v84, v8, v8
	v_fmac_f32_e32 v85, v10, v10
	v_fmac_f32_e32 v86, v4, v4
	v_fmac_f32_e32 v87, v6, v6
	v_fmac_f32_e32 v88, v0, v0
	v_fmac_f32_e32 v89, v2, v2
	v_add_f32_e32 v82, v82, v83
	v_add_f32_e32 v83, v84, v85
	v_add_f32_e32 v84, v86, v87
	v_add_f32_e32 v85, v88, v89
	s_waitcnt vmcnt(11)
	v_mul_f32_e32 v86, v61, v61
	v_mul_f32_e32 v87, v63, v63
	s_waitcnt vmcnt(10)
	v_mul_f32_e32 v88, v57, v57
	v_mul_f32_e32 v89, v59, v59
	s_waitcnt vmcnt(9)
	v_mul_f32_e32 v90, v53, v53
	v_mul_f32_e32 v91, v55, v55
	s_waitcnt vmcnt(8)
	v_mul_f32_e32 v92, v49, v49
	v_mul_f32_e32 v93, v51, v51
	v_add_f32_e32 v82, v82, v83
	v_fmac_f32_e32 v86, v60, v60
	v_fmac_f32_e32 v87, v62, v62
	v_fmac_f32_e32 v88, v56, v56
	v_fmac_f32_e32 v89, v58, v58
	v_fmac_f32_e32 v90, v52, v52
	v_fmac_f32_e32 v91, v54, v54
	v_fmac_f32_e32 v92, v48, v48
	v_fmac_f32_e32 v93, v50, v50
	s_waitcnt vmcnt(7)
	v_mul_f32_e32 v83, v45, v45
	v_mul_f32_e32 v94, v47, v47
	s_waitcnt vmcnt(6)
	v_mul_f32_e32 v95, v41, v41
	v_mul_f32_e32 v96, v43, v43
	s_waitcnt vmcnt(5)
	v_mul_f32_e32 v97, v37, v37
	v_mul_f32_e32 v98, v39, v39
	v_add_f32_e32 v82, v82, v84
	v_add_f32_e32 v84, v86, v87
	v_add_f32_e32 v86, v88, v89
	v_add_f32_e32 v87, v90, v91
	v_add_f32_e32 v88, v92, v93
	v_fmac_f32_e32 v83, v44, v44
	v_fmac_f32_e32 v94, v46, v46
	v_fmac_f32_e32 v95, v40, v40
	v_fmac_f32_e32 v96, v42, v42
	s_waitcnt vmcnt(3)
	v_mul_f32_e32 v89, v29, v29
	v_mul_f32_e32 v90, v31, v31
	s_waitcnt vmcnt(2)
	v_mul_f32_e32 v91, v25, v25
	v_mul_f32_e32 v92, v27, v27
	v_mul_f32_e32 v99, v33, v33
	v_mul_f32_e32 v100, v35, v35
	v_fmac_f32_e32 v97, v36, v36
	v_fmac_f32_e32 v98, v38, v38
	s_waitcnt vmcnt(1)
	v_mul_f32_e32 v93, v21, v21
	v_mul_f32_e32 v101, v23, v23
	s_waitcnt vmcnt(0)
; __device__ __forceinline__ float wave_sum(float v) { v += dpp_mov<0xB1>(v); v += dpp_mov<0x4E>(v); v += dpp_mov<0x141>(v); v += dpp_mov<0x140>(v); v = sum_x16(v); return sum_x32(v); }
; __global__ void __launch_bounds__(NWAVES * 64, 2) fwd_kernel(Args args) {
;     ...
;             for (int rr = 0; rr < 4; ++rr) {
;                 float s = 0.f;
; #pragma unroll
;                 for (int j = 0; j < 4; ++j) s += (v[rr][j].x * v[rr][j].x + v[rr][j].y * v[rr][j].y) + (v[rr][j].z * v[rr][j].z + v[rr][j].w * v[rr][j].w);
;                 s = wave_sum(s);
;                 const float rstd = __builtin_amdgcn_rsqf(s * (1.0f / DM) + pg8::RMS_EPS);
	v_mul_f32_e32 v102, v17, v17
	v_mul_f32_e32 v103, v19, v19
	v_add_f32_e32 v82, v82, v85
	v_add_f32_e32 v84, v84, v86
	v_add_f32_e32 v83, v83, v94
	v_add_f32_e32 v85, v95, v96
	v_fmac_f32_e32 v89, v28, v28
	v_fmac_f32_e32 v90, v30, v30
	v_fmac_f32_e32 v91, v24, v24
	v_fmac_f32_e32 v92, v26, v26
	v_mov_b32_e32 v74, v12
	v_mov_b32_e32 v75, v14
	v_mov_b32_e32 v76, v8
	v_mov_b32_e32 v77, v10
	v_mov_b32_e32 v78, v4
	v_mov_b32_e32 v14, v13
	v_mov_b32_e32 v10, v9
	v_mov_b32_e32 v4, v56
	v_mov_b32_e32 v8, v52
	v_mov_b32_e32 v9, v54
	v_mov_b32_e32 v12, v48
	v_mov_b32_e32 v13, v50
	v_mov_b32_e32 v54, v53
	v_mov_b32_e32 v50, v49
	v_mov_b32_e32 v48, v44
	v_mov_b32_e32 v49, v46
	v_mov_b32_e32 v52, v40
	v_mov_b32_e32 v53, v42
	v_mov_b32_e32 v56, v36
	v_fmac_f32_e32 v99, v32, v32
	v_fmac_f32_e32 v100, v34, v34
	v_mov_b32_e32 v46, v45
	v_mov_b32_e32 v42, v41
	v_mov_b32_e32 v36, v24
	v_mov_b32_e32 v40, v20
	v_mov_b32_e32 v41, v22
	v_mov_b32_e32 v44, v16
	v_mov_b32_e32 v45, v18
	v_add_f32_e32 v86, v97, v98
	v_fmac_f32_e32 v93, v20, v20
	v_fmac_f32_e32 v101, v22, v22
	v_fmac_f32_e32 v102, v16, v16
	v_fmac_f32_e32 v103, v18, v18
	v_mov_b32_e32 v22, v21
	v_mov_b32_e32 v18, v17
	v_add_f32_dpp v16, v82, v82 quad_perm:[1,0,3,2] row_mask:0xf bank_mask:0xf bound_ctrl:1
	v_add_f32_e32 v17, v84, v87
	v_add_f32_e32 v20, v83, v85
	v_add_f32_e32 v21, v89, v90
	v_add_f32_e32 v24, v91, v92
	v_mov_b32_e32 v79, v6
	v_mov_b32_e32 v6, v5
	v_mov_b32_e32 v5, v58
	v_mov_b32_e32 v58, v57
	v_mov_b32_e32 v57, v38
	v_mov_b32_e32 v38, v37
	v_mov_b32_e32 v37, v26
	v_add_f32_e32 v94, v99, v100
	v_mov_b32_e32 v26, v25
	v_add_f32_e32 v25, v93, v101
	v_add_f32_dpp v16, v16, v16 quad_perm:[2,3,0,1] row_mask:0xf bank_mask:0xf bound_ctrl:1
	v_add_f32_e32 v17, v17, v88
	v_add_f32_e32 v20, v20, v86
	v_add_f32_e32 v21, v21, v24
	v_mov_b32_e32 v80, v0
	v_mov_b32_e32 v0, v60
	v_mov_b32_e32 v60, v32
	v_mov_b32_e32 v32, v28
	v_add_f32_e32 v28, v102, v103
	v_add_f32_dpp v16, v16, v16 row_half_mirror row_mask:0xf bank_mask:0xf bound_ctrl:1
	v_add_f32_dpp v17, v17, v17 quad_perm:[1,0,3,2] row_mask:0xf bank_mask:0xf bound_ctrl:1
	v_add_f32_e32 v20, v20, v94
	v_add_f32_e32 v21, v21, v25
	v_add_f32_dpp v16, v16, v16 row_mirror row_mask:0xf bank_mask:0xf bound_ctrl:1
	v_add_f32_dpp v17, v17, v17 quad_perm:[2,3,0,1] row_mask:0xf bank_mask:0xf bound_ctrl:1
	v_add_f32_dpp v20, v20, v20 quad_perm:[1,0,3,2] row_mask:0xf bank_mask:0xf bound_ctrl:1
	v_add_f32_e32 v21, v21, v28
	v_mov_b32_e32 v24, v16
	v_add_f32_dpp v17, v17, v17 row_half_mirror row_mask:0xf bank_mask:0xf bound_ctrl:1
	v_add_f32_dpp v20, v20, v20 quad_perm:[2,3,0,1] row_mask:0xf bank_mask:0xf bound_ctrl:1
	v_add_f32_dpp v21, v21, v21 quad_perm:[1,0,3,2] row_mask:0xf bank_mask:0xf bound_ctrl:1
	v_permlane16_swap_b32_e32 v16, v24
	v_add_f32_dpp v17, v17, v17 row_mirror row_mask:0xf bank_mask:0xf bound_ctrl:1
	v_add_f32_dpp v20, v20, v20 row_half_mirror row_mask:0xf bank_mask:0xf bound_ctrl:1
	v_add_f32_dpp v21, v21, v21 quad_perm:[2,3,0,1] row_mask:0xf bank_mask:0xf bound_ctrl:1
	v_add_f32_e32 v16, v16, v24
	v_mov_b32_e32 v24, v17
	v_add_f32_dpp v20, v20, v20 row_mirror row_mask:0xf bank_mask:0xf bound_ctrl:1
	v_add_f32_dpp v21, v21, v21 row_half_mirror row_mask:0xf bank_mask:0xf bound_ctrl:1
	v_mov_b32_e32 v25, v16
	v_permlane16_swap_b32_e32 v17, v24
	v_mov_b32_e32 v28, v20
	v_add_f32_dpp v21, v21, v21 row_mirror row_mask:0xf bank_mask:0xf bound_ctrl:1
	v_permlane32_swap_b32_e32 v16, v25
	v_add_f32_e32 v17, v17, v24
	v_permlane16_swap_b32_e32 v20, v28
	v_mov_b32_e32 v24, v21
	v_add_f32_e32 v16, v16, v25
	v_mov_b32_e32 v25, v17
	v_add_f32_e32 v20, v20, v28
	v_permlane16_swap_b32_e32 v21, v24
	v_fmamk_f32 v16, v16, 0x3a800000, v65
	v_permlane32_swap_b32_e32 v17, v25
	v_mov_b32_e32 v28, v20
	v_add_f32_e32 v21, v21, v24
	v_rsq_f32_e32 v16, v16
	v_add_f32_e32 v17, v17, v25
	v_permlane32_swap_b32_e32 v20, v28
	v_mov_b32_e32 v24, v21
	v_fmamk_f32 v17, v17, 0x3a800000, v65
	v_add_f32_e32 v25, v20, v28
	v_permlane32_swap_b32_e32 v21, v24
	v_rsq_f32_e32 v20, v17
	v_fmamk_f32 v17, v25, 0x3a800000, v65
	v_add_f32_e32 v21, v21, v24
	v_rsq_f32_e32 v24, v17
	v_fmamk_f32 v17, v21, 0x3a800000, v65
	v_mov_b32_e32 v81, v2
	v_mov_b32_e32 v2, v1
	v_mov_b32_e32 v1, v62
	v_mov_b32_e32 v62, v61
	v_mov_b32_e32 v61, v34
	v_mov_b32_e32 v34, v33
	v_mov_b32_e32 v33, v30
	v_mov_b32_e32 v30, v29
	v_pk_mul_f32 v[28:29], v[16:17], v[74:75] op_sel_hi:[0,1]
	v_pk_mul_f32 v[14:15], v[16:17], v[14:15] op_sel_hi:[0,1]
	v_pk_mul_f32 v[74:75], v[16:17], v[76:77] op_sel_hi:[0,1]
	v_pk_mul_f32 v[6:7], v[16:17], v[6:7] op_sel_hi:[0,1]
	v_pk_mul_f32 v[2:3], v[16:17], v[2:3] op_sel_hi:[0,1]
	v_and_b32_sdwa v21, v28, v73 dst_sel:DWORD dst_unused:UNUSED_PAD src0_sel:WORD_1 src1_sel:DWORD
	v_and_b32_sdwa v25, v15, v73 dst_sel:DWORD dst_unused:UNUSED_PAD src0_sel:WORD_1 src1_sel:DWORD
	v_pk_mul_f32 v[10:11], v[16:17], v[10:11] op_sel_hi:[0,1]
	v_pk_mul_f32 v[76:77], v[16:17], v[78:79] op_sel_hi:[0,1]
	v_pk_mul_f32 v[78:79], v[16:17], v[80:81] op_sel_hi:[0,1]
	v_rsq_f32_e32 v16, v17
	v_and_b32_sdwa v80, v14, v73 dst_sel:DWORD dst_unused:UNUSED_PAD src0_sel:WORD_1 src1_sel:DWORD
	v_and_b32_sdwa v82, v74, v73 dst_sel:DWORD dst_unused:UNUSED_PAD src0_sel:WORD_1 src1_sel:DWORD
	v_and_b32_sdwa v87, v7, v73 dst_sel:DWORD dst_unused:UNUSED_PAD src0_sel:WORD_1 src1_sel:DWORD
	v_and_b32_sdwa v91, v3, v73 dst_sel:DWORD dst_unused:UNUSED_PAD src0_sel:WORD_1 src1_sel:DWORD
	v_add3_u32 v93, v28, v21, s2
	v_add3_u32 v21, v15, v25, s2
	v_and_b32_sdwa v17, v29, v73 dst_sel:DWORD dst_unused:UNUSED_PAD src0_sel:WORD_1 src1_sel:DWORD
	v_and_b32_sdwa v81, v75, v73 dst_sel:DWORD dst_unused:UNUSED_PAD src0_sel:WORD_1 src1_sel:DWORD
; __device__ __forceinline__ unsigned f2bf(float f) { unsigned u = __builtin_bit_cast(unsigned, f); return (u + 0x7fffu + ((u >> 16) & 1u)) >> 16; }
; __device__ __forceinline__ unsigned pk2(float lo, float hi) { return f2bf(lo) | (f2bf(hi) << 16); }
; __global__ void __launch_bounds__(NWAVES * 64, 2) fwd_kernel(Args args) {
;     ...
;                 for (int j = 0; j < 4; ++j) { v2u w; w.x = pk2(v[rr][j].x * rstd, v[rr][j].y * rstd); w.y = pk2(v[rr][j].z * rstd, v[rr][j].w * rstd); o8[64 * j] = w; }
	v_and_b32_sdwa v83, v11, v73 dst_sel:DWORD dst_unused:UNUSED_PAD src0_sel:WORD_1 src1_sel:DWORD
	v_and_b32_sdwa v84, v10, v73 dst_sel:DWORD dst_unused:UNUSED_PAD src0_sel:WORD_1 src1_sel:DWORD
	v_and_b32_sdwa v88, v6, v73 dst_sel:DWORD dst_unused:UNUSED_PAD src0_sel:WORD_1 src1_sel:DWORD
	v_and_b32_sdwa v92, v2, v73 dst_sel:DWORD dst_unused:UNUSED_PAD src0_sel:WORD_1 src1_sel:DWORD
	v_add3_u32 v25, v14, v80, s2
	v_add3_u32 v74, v74, v82, s2
	v_add3_u32 v80, v7, v87, s2
	v_add3_u32 v82, v3, v91, s2
	v_pk_mul_f32 v[0:1], v[20:21], v[0:1] op_sel_hi:[0,1]
	v_and_b32_sdwa v85, v77, v73 dst_sel:DWORD dst_unused:UNUSED_PAD src0_sel:WORD_1 src1_sel:DWORD
	v_and_b32_sdwa v86, v76, v73 dst_sel:DWORD dst_unused:UNUSED_PAD src0_sel:WORD_1 src1_sel:DWORD
	v_and_b32_sdwa v89, v79, v73 dst_sel:DWORD dst_unused:UNUSED_PAD src0_sel:WORD_1 src1_sel:DWORD
	v_and_b32_sdwa v90, v78, v73 dst_sel:DWORD dst_unused:UNUSED_PAD src0_sel:WORD_1 src1_sel:DWORD
	v_add3_u32 v17, v29, v17, s2
	v_add3_u32 v75, v75, v81, s2
	v_add3_u32 v28, v11, v83, s2
	v_add3_u32 v29, v10, v84, s2
	v_add3_u32 v81, v6, v88, s2
	v_add3_u32 v83, v2, v92, s2
	v_pk_mul_f32 v[2:3], v[20:21], v[62:63] op_sel_hi:[0,1]
	v_pk_mul_f32 v[4:5], v[20:21], v[4:5] op_sel_hi:[0,1]
	v_pk_mul_f32 v[6:7], v[20:21], v[58:59] op_sel_hi:[0,1]
	v_pk_mul_f32 v[10:11], v[20:21], v[54:55] op_sel_hi:[0,1]
	v_pk_mul_f32 v[14:15], v[20:21], v[50:51] op_sel_hi:[0,1]
	v_and_b32_e32 v54, 0xffff0000, v21
	v_and_b32_e32 v62, 0xffff0000, v80
	v_and_b32_e32 v80, 0xffff0000, v82
	v_and_b32_sdwa v82, v1, v73 dst_sel:DWORD dst_unused:UNUSED_PAD src0_sel:WORD_1 src1_sel:DWORD
	v_add3_u32 v76, v76, v86, s2
	v_add3_u32 v77, v77, v85, s2
	v_add3_u32 v78, v78, v90, s2
	v_add3_u32 v79, v79, v89, s2
	v_pk_mul_f32 v[8:9], v[20:21], v[8:9] op_sel_hi:[0,1]
	v_pk_mul_f32 v[12:13], v[20:21], v[12:13] op_sel_hi:[0,1]
	v_and_b32_e32 v55, 0xffff0000, v25
	v_and_b32_e32 v58, 0xffff0000, v28
	v_and_b32_e32 v59, 0xffff0000, v29
	v_and_b32_e32 v63, 0xffff0000, v81
	v_and_b32_e32 v81, 0xffff0000, v83
	v_and_b32_sdwa v83, v0, v73 dst_sel:DWORD dst_unused:UNUSED_PAD src0_sel:WORD_1 src1_sel:DWORD
	v_and_b32_sdwa v84, v3, v73 dst_sel:DWORD dst_unused:UNUSED_PAD src0_sel:WORD_1 src1_sel:DWORD
	v_and_b32_sdwa v85, v2, v73 dst_sel:DWORD dst_unused:UNUSED_PAD src0_sel:WORD_1 src1_sel:DWORD
	v_and_b32_sdwa v86, v5, v73 dst_sel:DWORD dst_unused:UNUSED_PAD src0_sel:WORD_1 src1_sel:DWORD
	v_and_b32_sdwa v88, v7, v73 dst_sel:DWORD dst_unused:UNUSED_PAD src0_sel:WORD_1 src1_sel:DWORD
	v_and_b32_sdwa v89, v6, v73 dst_sel:DWORD dst_unused:UNUSED_PAD src0_sel:WORD_1 src1_sel:DWORD
	v_and_b32_sdwa v92, v11, v73 dst_sel:DWORD dst_unused:UNUSED_PAD src0_sel:WORD_1 src1_sel:DWORD
	v_and_b32_sdwa v94, v10, v73 dst_sel:DWORD dst_unused:UNUSED_PAD src0_sel:WORD_1 src1_sel:DWORD
	v_and_b32_sdwa v97, v15, v73 dst_sel:DWORD dst_unused:UNUSED_PAD src0_sel:WORD_1 src1_sel:DWORD
	v_and_b32_sdwa v98, v14, v73 dst_sel:DWORD dst_unused:UNUSED_PAD src0_sel:WORD_1 src1_sel:DWORD
	v_pk_mul_f32 v[20:21], v[24:25], v[48:49] op_sel_hi:[0,1]
	v_pk_mul_f32 v[28:29], v[24:25], v[46:47] op_sel_hi:[0,1]
	v_pk_mul_f32 v[46:47], v[24:25], v[52:53] op_sel_hi:[0,1]
	v_pk_mul_f32 v[42:43], v[24:25], v[42:43] op_sel_hi:[0,1]
	v_pk_mul_f32 v[48:49], v[24:25], v[56:57] op_sel_hi:[0,1]
	v_pk_mul_f32 v[38:39], v[24:25], v[38:39] op_sel_hi:[0,1]
	v_pk_mul_f32 v[50:51], v[24:25], v[60:61] op_sel_hi:[0,1]
	v_pk_mul_f32 v[24:25], v[24:25], v[34:35] op_sel_hi:[0,1]
	v_or_b32_sdwa v35, v54, v17 dst_sel:DWORD dst_unused:UNUSED_PAD src0_sel:DWORD src1_sel:WORD_1
	v_add3_u32 v17, v1, v82, s2
	v_and_b32_sdwa v87, v4, v73 dst_sel:DWORD dst_unused:UNUSED_PAD src0_sel:WORD_1 src1_sel:DWORD
	v_and_b32_sdwa v90, v9, v73 dst_sel:DWORD dst_unused:UNUSED_PAD src0_sel:WORD_1 src1_sel:DWORD
	v_and_b32_sdwa v91, v8, v73 dst_sel:DWORD dst_unused:UNUSED_PAD src0_sel:WORD_1 src1_sel:DWORD
	v_and_b32_sdwa v95, v13, v73 dst_sel:DWORD dst_unused:UNUSED_PAD src0_sel:WORD_1 src1_sel:DWORD
	v_and_b32_sdwa v96, v12, v73 dst_sel:DWORD dst_unused:UNUSED_PAD src0_sel:WORD_1 src1_sel:DWORD
	v_or_b32_sdwa v34, v55, v93 dst_sel:DWORD dst_unused:UNUSED_PAD src0_sel:DWORD src1_sel:WORD_1
	v_or_b32_sdwa v53, v58, v75 dst_sel:DWORD dst_unused:UNUSED_PAD src0_sel:DWORD src1_sel:WORD_1
	v_or_b32_sdwa v52, v59, v74 dst_sel:DWORD dst_unused:UNUSED_PAD src0_sel:DWORD src1_sel:WORD_1
	v_or_b32_sdwa v55, v62, v77 dst_sel:DWORD dst_unused:UNUSED_PAD src0_sel:DWORD src1_sel:WORD_1
	v_or_b32_sdwa v54, v63, v76 dst_sel:DWORD dst_unused:UNUSED_PAD src0_sel:DWORD src1_sel:WORD_1
	v_or_b32_sdwa v56, v81, v78 dst_sel:DWORD dst_unused:UNUSED_PAD src0_sel:DWORD src1_sel:WORD_1
	v_add3_u32 v58, v0, v83, s2
	v_add3_u32 v59, v3, v84, s2
	v_add3_u32 v60, v2, v85, s2
	v_add3_u32 v62, v5, v86, s2
	v_add3_u32 v63, v7, v88, s2
	v_add3_u32 v74, v6, v89, s2
	v_add3_u32 v77, v11, v92, s2
	v_add3_u32 v78, v10, v94, s2
	v_add3_u32 v81, v15, v97, s2
	v_add3_u32 v82, v14, v98, s2
	v_and_b32_sdwa v85, v29, v73 dst_sel:DWORD dst_unused:UNUSED_PAD src0_sel:WORD_1 src1_sel:DWORD
	v_and_b32_sdwa v86, v28, v73 dst_sel:DWORD dst_unused:UNUSED_PAD src0_sel:WORD_1 src1_sel:DWORD
	v_and_b32_sdwa v88, v46, v73 dst_sel:DWORD dst_unused:UNUSED_PAD src0_sel:WORD_1 src1_sel:DWORD
	v_and_b32_sdwa v89, v43, v73 dst_sel:DWORD dst_unused:UNUSED_PAD src0_sel:WORD_1 src1_sel:DWORD
	v_and_b32_sdwa v93, v39, v73 dst_sel:DWORD dst_unused:UNUSED_PAD src0_sel:WORD_1 src1_sel:DWORD
	v_and_b32_sdwa v94, v38, v73 dst_sel:DWORD dst_unused:UNUSED_PAD src0_sel:WORD_1 src1_sel:DWORD
	v_pk_mul_f32 v[0:1], v[16:17], v[32:33] op_sel_hi:[0,1]
	v_pk_mul_f32 v[2:3], v[16:17], v[30:31] op_sel_hi:[0,1]
; #define GAS __attribute__((address_space(1)))
; __device__ __forceinline__ unsigned f2bf(float f) { unsigned u = __builtin_bit_cast(unsigned, f); return (u + 0x7fffu + ((u >> 16) & 1u)) >> 16; }
; __device__ __forceinline__ unsigned pk2(float lo, float hi) { return f2bf(lo) | (f2bf(hi) << 16); }
; __global__ void __launch_bounds__(NWAVES * 64, 2) fwd_kernel(Args args) {
;     ...
;                 GAS v2u* o8 = (GAS v2u*)(XB + (size_t)(m0 + rr) * DM) + F.lane;
; #pragma unroll
;                 for (int j = 0; j < 4; ++j) { v2u w; w.x = pk2(v[rr][j].x * rstd, v[rr][j].y * rstd); w.y = pk2(v[rr][j].z * rstd, v[rr][j].w * rstd); o8[64 * j] = w; }
	v_or_b32_sdwa v57, v80, v79 dst_sel:DWORD dst_unused:UNUSED_PAD src0_sel:DWORD src1_sel:WORD_1
	v_add3_u32 v61, v4, v87, s2
	v_add3_u32 v75, v8, v91, s2
	v_add3_u32 v76, v9, v90, s2
	v_add3_u32 v79, v12, v96, s2
	v_add3_u32 v80, v13, v95, s2
	v_and_b32_sdwa v83, v21, v73 dst_sel:DWORD dst_unused:UNUSED_PAD src0_sel:WORD_1 src1_sel:DWORD
	v_and_b32_sdwa v84, v20, v73 dst_sel:DWORD dst_unused:UNUSED_PAD src0_sel:WORD_1 src1_sel:DWORD
	v_and_b32_sdwa v87, v47, v73 dst_sel:DWORD dst_unused:UNUSED_PAD src0_sel:WORD_1 src1_sel:DWORD
	v_and_b32_sdwa v90, v42, v73 dst_sel:DWORD dst_unused:UNUSED_PAD src0_sel:WORD_1 src1_sel:DWORD
	v_and_b32_sdwa v91, v49, v73 dst_sel:DWORD dst_unused:UNUSED_PAD src0_sel:WORD_1 src1_sel:DWORD
	v_and_b32_sdwa v96, v50, v73 dst_sel:DWORD dst_unused:UNUSED_PAD src0_sel:WORD_1 src1_sel:DWORD
	v_and_b32_sdwa v97, v25, v73 dst_sel:DWORD dst_unused:UNUSED_PAD src0_sel:WORD_1 src1_sel:DWORD
	v_and_b32_sdwa v98, v24, v73 dst_sel:DWORD dst_unused:UNUSED_PAD src0_sel:WORD_1 src1_sel:DWORD
	v_pk_mul_f32 v[4:5], v[16:17], v[36:37] op_sel_hi:[0,1]
	v_pk_mul_f32 v[6:7], v[16:17], v[26:27] op_sel_hi:[0,1]
	v_pk_mul_f32 v[8:9], v[16:17], v[40:41] op_sel_hi:[0,1]
	v_pk_mul_f32 v[10:11], v[16:17], v[22:23] op_sel_hi:[0,1]
	v_pk_mul_f32 v[12:13], v[16:17], v[44:45] op_sel_hi:[0,1]
	v_pk_mul_f32 v[14:15], v[16:17], v[18:19] op_sel_hi:[0,1]
	global_store_dwordx2 v[66:67], v[34:35], off
	global_store_dwordx2 v[66:67], v[52:53], off offset:512
	global_store_dwordx2 v[66:67], v[54:55], off offset:1024
	global_store_dwordx2 v[66:67], v[56:57], off offset:1536
	v_and_b32_e32 v16, 0xffff0000, v59
	v_and_b32_e32 v18, 0xffff0000, v60
	v_and_b32_e32 v22, 0xffff0000, v74
	v_and_b32_e32 v23, 0xffff0000, v77
	v_and_b32_e32 v26, 0xffff0000, v78
	v_and_b32_e32 v27, 0xffff0000, v81
	v_and_b32_e32 v30, 0xffff0000, v82
	v_add3_u32 v29, v29, v85, s2
	v_add3_u32 v28, v28, v86, s2
	v_add3_u32 v33, v46, v88, s2
	v_add3_u32 v35, v43, v89, s2
	v_add3_u32 v39, v39, v93, s2
	v_add3_u32 v38, v38, v94, s2
	v_and_b32_sdwa v43, v1, v73 dst_sel:DWORD dst_unused:UNUSED_PAD src0_sel:WORD_1 src1_sel:DWORD
	v_and_b32_sdwa v45, v3, v73 dst_sel:DWORD dst_unused:UNUSED_PAD src0_sel:WORD_1 src1_sel:DWORD
	v_and_b32_sdwa v46, v2, v73 dst_sel:DWORD dst_unused:UNUSED_PAD src0_sel:WORD_1 src1_sel:DWORD
	v_and_b32_sdwa v92, v48, v73 dst_sel:DWORD dst_unused:UNUSED_PAD src0_sel:WORD_1 src1_sel:DWORD
	v_and_b32_sdwa v95, v51, v73 dst_sel:DWORD dst_unused:UNUSED_PAD src0_sel:WORD_1 src1_sel:DWORD
	v_and_b32_e32 v19, 0xffff0000, v63
	v_add3_u32 v31, v20, v84, s2
	v_add3_u32 v32, v21, v83, s2
	v_add3_u32 v34, v47, v87, s2
	v_add3_u32 v36, v42, v90, s2
	v_add3_u32 v40, v49, v91, s2
	v_add3_u32 v41, v50, v96, s2
	v_add3_u32 v25, v25, v97, s2
	v_add3_u32 v24, v24, v98, s2
	v_and_b32_sdwa v44, v0, v73 dst_sel:DWORD dst_unused:UNUSED_PAD src0_sel:WORD_1 src1_sel:DWORD
	v_and_b32_sdwa v47, v5, v73 dst_sel:DWORD dst_unused:UNUSED_PAD src0_sel:WORD_1 src1_sel:DWORD
	v_and_b32_sdwa v49, v7, v73 dst_sel:DWORD dst_unused:UNUSED_PAD src0_sel:WORD_1 src1_sel:DWORD
	v_and_b32_sdwa v50, v6, v73 dst_sel:DWORD dst_unused:UNUSED_PAD src0_sel:WORD_1 src1_sel:DWORD
	v_and_b32_sdwa v53, v11, v73 dst_sel:DWORD dst_unused:UNUSED_PAD src0_sel:WORD_1 src1_sel:DWORD
	v_and_b32_sdwa v54, v10, v73 dst_sel:DWORD dst_unused:UNUSED_PAD src0_sel:WORD_1 src1_sel:DWORD
	v_and_b32_sdwa v57, v15, v73 dst_sel:DWORD dst_unused:UNUSED_PAD src0_sel:WORD_1 src1_sel:DWORD
	v_and_b32_sdwa v59, v14, v73 dst_sel:DWORD dst_unused:UNUSED_PAD src0_sel:WORD_1 src1_sel:DWORD
	v_or_b32_sdwa v17, v16, v17 dst_sel:DWORD dst_unused:UNUSED_PAD src0_sel:DWORD src1_sel:WORD_1
	v_or_b32_sdwa v16, v18, v58 dst_sel:DWORD dst_unused:UNUSED_PAD src0_sel:DWORD src1_sel:WORD_1
	v_or_b32_sdwa v18, v22, v61 dst_sel:DWORD dst_unused:UNUSED_PAD src0_sel:DWORD src1_sel:WORD_1
	v_or_b32_sdwa v21, v23, v76 dst_sel:DWORD dst_unused:UNUSED_PAD src0_sel:DWORD src1_sel:WORD_1
	v_or_b32_sdwa v20, v26, v75 dst_sel:DWORD dst_unused:UNUSED_PAD src0_sel:DWORD src1_sel:WORD_1
	v_or_b32_sdwa v23, v27, v80 dst_sel:DWORD dst_unused:UNUSED_PAD src0_sel:DWORD src1_sel:WORD_1
; #define GAS __attribute__((address_space(1)))
; __device__ __forceinline__ unsigned pk2(float lo, float hi) { return f2bf(lo) | (f2bf(hi) << 16); }
; __global__ void __launch_bounds__(NWAVES * 64, 2) fwd_kernel(Args args) {
;     ...
;                 GAS v2u* o8 = (GAS v2u*)(XB + (size_t)(m0 + rr) * DM) + F.lane;
; #pragma unroll
;                 for (int j = 0; j < 4; ++j) { v2u w; w.x = pk2(v[rr][j].x * rstd, v[rr][j].y * rstd); w.y = pk2(v[rr][j].z * rstd, v[rr][j].w * rstd); o8[64 * j] = w; }
;             }
	v_or_b32_sdwa v22, v30, v79 dst_sel:DWORD dst_unused:UNUSED_PAD src0_sel:DWORD src1_sel:WORD_1
	v_and_b32_e32 v26, 0xffff0000, v29
	v_and_b32_e32 v27, 0xffff0000, v28
	v_and_b32_e32 v28, 0xffff0000, v35
	v_and_b32_e32 v30, 0xffff0000, v39
	v_and_b32_e32 v35, 0xffff0000, v38
	v_add3_u32 v38, v1, v43, s2
	v_add3_u32 v39, v3, v45, s2
	v_add3_u32 v43, v2, v46, s2
	v_add3_u32 v37, v48, v92, s2
	v_add3_u32 v42, v51, v95, s2
	v_and_b32_sdwa v48, v4, v73 dst_sel:DWORD dst_unused:UNUSED_PAD src0_sel:WORD_1 src1_sel:DWORD
	v_and_b32_sdwa v51, v9, v73 dst_sel:DWORD dst_unused:UNUSED_PAD src0_sel:WORD_1 src1_sel:DWORD
	v_and_b32_sdwa v52, v8, v73 dst_sel:DWORD dst_unused:UNUSED_PAD src0_sel:WORD_1 src1_sel:DWORD
	v_and_b32_sdwa v55, v13, v73 dst_sel:DWORD dst_unused:UNUSED_PAD src0_sel:WORD_1 src1_sel:DWORD
	v_and_b32_sdwa v56, v12, v73 dst_sel:DWORD dst_unused:UNUSED_PAD src0_sel:WORD_1 src1_sel:DWORD
	v_or_b32_sdwa v19, v19, v62 dst_sel:DWORD dst_unused:UNUSED_PAD src0_sel:DWORD src1_sel:WORD_1
	v_and_b32_e32 v29, 0xffff0000, v36
	v_and_b32_e32 v25, 0xffff0000, v25
	v_and_b32_e32 v24, 0xffff0000, v24
	v_add3_u32 v36, v0, v44, s2
	v_add3_u32 v45, v5, v47, s2
	v_add3_u32 v46, v7, v49, s2
	v_add3_u32 v47, v6, v50, s2
	v_add3_u32 v11, v11, v53, s2
	v_add3_u32 v10, v10, v54, s2
	v_add3_u32 v15, v15, v57, s2
	v_add3_u32 v14, v14, v59, s2
	global_store_dwordx2 v[66:67], v[16:17], off offset:2048
	global_store_dwordx2 v[66:67], v[18:19], off offset:2560
	global_store_dwordx2 v[66:67], v[20:21], off offset:3072
	global_store_dwordx2 v[66:67], v[22:23], off offset:3584
	v_or_b32_sdwa v1, v26, v32 dst_sel:DWORD dst_unused:UNUSED_PAD src0_sel:DWORD src1_sel:WORD_1
	v_or_b32_sdwa v0, v27, v31 dst_sel:DWORD dst_unused:UNUSED_PAD src0_sel:DWORD src1_sel:WORD_1
	v_and_b32_e32 v16, 0xffff0000, v39
	v_and_b32_e32 v17, 0xffff0000, v43
	v_add3_u32 v44, v4, v48, s2
	v_add3_u32 v8, v8, v52, s2
	v_add3_u32 v9, v9, v51, s2
	v_add3_u32 v12, v12, v56, s2
	v_add3_u32 v13, v13, v55, s2
	v_or_b32_sdwa v3, v28, v34 dst_sel:DWORD dst_unused:UNUSED_PAD src0_sel:DWORD src1_sel:WORD_1
	v_or_b32_sdwa v2, v29, v33 dst_sel:DWORD dst_unused:UNUSED_PAD src0_sel:DWORD src1_sel:WORD_1
	v_or_b32_sdwa v5, v30, v40 dst_sel:DWORD dst_unused:UNUSED_PAD src0_sel:DWORD src1_sel:WORD_1
	v_or_b32_sdwa v4, v35, v37 dst_sel:DWORD dst_unused:UNUSED_PAD src0_sel:DWORD src1_sel:WORD_1
	v_or_b32_sdwa v7, v25, v42 dst_sel:DWORD dst_unused:UNUSED_PAD src0_sel:DWORD src1_sel:WORD_1
	v_or_b32_sdwa v6, v24, v41 dst_sel:DWORD dst_unused:UNUSED_PAD src0_sel:DWORD src1_sel:WORD_1
	v_and_b32_e32 v18, 0xffff0000, v46
	v_and_b32_e32 v19, 0xffff0000, v47
	v_and_b32_e32 v11, 0xffff0000, v11
	v_and_b32_e32 v10, 0xffff0000, v10
	v_and_b32_e32 v15, 0xffff0000, v15
	v_and_b32_e32 v14, 0xffff0000, v14
	v_lshl_add_u64 v[66:67], v[66:67], 0, s[6:7]
	global_store_dwordx2 v[70:71], v[0:1], off
	global_store_dwordx2 v[70:71], v[2:3], off offset:512
	global_store_dwordx2 v[70:71], v[4:5], off offset:1024
	global_store_dwordx2 v[70:71], v[6:7], off offset:1536
	v_or_b32_sdwa v1, v16, v38 dst_sel:DWORD dst_unused:UNUSED_PAD src0_sel:DWORD src1_sel:WORD_1
	v_or_b32_sdwa v0, v17, v36 dst_sel:DWORD dst_unused:UNUSED_PAD src0_sel:DWORD src1_sel:WORD_1
	v_or_b32_sdwa v3, v18, v45 dst_sel:DWORD dst_unused:UNUSED_PAD src0_sel:DWORD src1_sel:WORD_1
	v_or_b32_sdwa v2, v19, v44 dst_sel:DWORD dst_unused:UNUSED_PAD src0_sel:DWORD src1_sel:WORD_1
	v_or_b32_sdwa v5, v11, v9 dst_sel:DWORD dst_unused:UNUSED_PAD src0_sel:DWORD src1_sel:WORD_1
	v_or_b32_sdwa v4, v10, v8 dst_sel:DWORD dst_unused:UNUSED_PAD src0_sel:DWORD src1_sel:WORD_1
	v_or_b32_sdwa v7, v15, v13 dst_sel:DWORD dst_unused:UNUSED_PAD src0_sel:DWORD src1_sel:WORD_1
	v_or_b32_sdwa v6, v14, v12 dst_sel:DWORD dst_unused:UNUSED_PAD src0_sel:DWORD src1_sel:WORD_1
	global_store_dwordx2 v[70:71], v[0:1], off offset:2048
	global_store_dwordx2 v[70:71], v[2:3], off offset:2560
	global_store_dwordx2 v[70:71], v[4:5], off offset:3072
	global_store_dwordx2 v[70:71], v[6:7], off offset:3584
	s_cbranch_scc0 .LBB0_60
